# NSA top-n selection: 30 serial ds_bpermute lane exchanges replaced by DPP moves (quad_perm / row_half_mirror), on top of v35
# speedup vs baseline: 1.0048x; 1.0033x over previous
.LBB0_943:
	s_or_b64 exec, exec, s[4:5]
	v_add_u32_e32 v0, 0xa804, v197
	v_add_u32_e32 v2, 0xc904, v197
	ds_read2_b32 v[0:1], v0 offset1:1
	ds_read2_b32 v[2:3], v2 offset1:1
	v_add_u32_e32 v5, 0xea04, v197
	v_add_u32_e32 v8, 0x6304, v198
	ds_read2_b32 v[6:7], v5 offset1:1
	ds_read2_b32 v[8:9], v8 offset1:1
	ds_read_b32 v10, v197 offset:59916
	ds_read_b32 v11, v198 offset:25356
	v_cmp_gt_u32_e32 vcc, s2, v196
	s_waitcnt lgkmcnt(4)
	v_add_f32_e32 v0, v0, v2
	s_waitcnt lgkmcnt(3)
	v_add_f32_e32 v0, v0, v6
	s_waitcnt lgkmcnt(2)
	v_add_f32_e32 v0, v0, v8
	v_cndmask_b32_e32 v5, -1.0, v0, vcc
	v_add_u32_e32 v0, 12, v197
	v_add_f32_e32 v2, v1, v3
	ds_read2st64_b32 v[0:1], v0 offset0:168 offset1:201
	v_add_f32_e32 v2, v2, v7
	v_add_f32_e32 v2, v2, v9
	v_cmp_ge_u32_e32 vcc, s2, v200
	s_waitcnt lgkmcnt(0)
	v_add_f32_e32 v0, v0, v1
	v_add_f32_e32 v0, v0, v10
	v_cndmask_b32_e32 v6, -1.0, v2, vcc
	v_add_f32_e32 v0, v0, v11
	v_cmp_ge_u32_e32 vcc, s2, v201
	s_nop 1
	v_cndmask_b32_e32 v7, -1.0, v0, vcc
	v_and_b32_e32 v0, 64, v211
	v_cmp_gt_f32_e32 vcc, v5, v4
	v_add_u32_e32 v3, 64, v0
	s_nop 0
	v_cndmask_b32_e32 v0, v4, v5, vcc
	v_cndmask_b32_e32 v1, v196, v199, vcc
	v_cmp_gt_f32_e32 vcc, v6, v0
	s_nop 1
	v_cndmask_b32_e32 v0, v0, v6, vcc
	v_cndmask_b32_e32 v9, v1, v200, vcc
	v_cmp_gt_f32_e32 vcc, v7, v0
	s_nop 1
	v_cndmask_b32_e32 v8, v0, v7, vcc
	v_xor_b32_e32 v0, 1, v211
	v_cmp_lt_i32_e64 s[14:15], v0, v3
	s_nop 1
	v_cndmask_b32_e64 v0, v211, v0, s[14:15]
	v_lshlrev_b32_e32 v1, 2, v0
	s_nop 1
	v_mov_b32_dpp v2, v8 quad_perm:[1,0,3,2] row_mask:0xf bank_mask:0xf
	v_cndmask_b32_e32 v0, v9, v201, vcc
	s_nop 1
	v_mov_b32_dpp v9, v0 quad_perm:[1,0,3,2] row_mask:0xf bank_mask:0xf
	s_waitcnt lgkmcnt(1)
	v_cmp_lt_f32_e64 s[4:5], v8, v2
	v_cmp_nlt_f32_e32 vcc, v8, v2
	s_and_saveexec_b64 s[16:17], vcc
	s_cbranch_execz .LBB0_945
	v_cmp_eq_f32_e32 vcc, v8, v2
	s_waitcnt lgkmcnt(0)
	v_cmp_lt_i32_e64 s[14:15], v9, v0
	s_and_b64 s[2:3], vcc, s[14:15]
	s_andn2_b64 s[4:5], s[4:5], exec
	s_and_b64 s[2:3], s[2:3], exec
	s_or_b64 s[4:5], s[4:5], s[2:3]

.LBB0_947:
	s_or_b64 exec, exec, s[14:15]
	v_xor_b32_e32 v2, 2, v211
	v_cmp_lt_i32_e32 vcc, v2, v3
	s_nop 1
	v_cndmask_b32_e32 v2, v211, v2, vcc
	v_lshlrev_b32_e32 v2, 2, v2
	s_nop 1
	v_mov_b32_dpp v10, v8 quad_perm:[2,3,0,1] row_mask:0xf bank_mask:0xf
	s_waitcnt lgkmcnt(1)
	s_nop 1
	v_mov_b32_dpp v9, v0 quad_perm:[2,3,0,1] row_mask:0xf bank_mask:0xf
	s_waitcnt lgkmcnt(1)
	v_cmp_lt_f32_e64 s[4:5], v8, v10
	v_cmp_nlt_f32_e32 vcc, v8, v10
	s_and_saveexec_b64 s[16:17], vcc
	s_cbranch_execz .LBB0_949
	v_cmp_eq_f32_e32 vcc, v8, v10
	s_waitcnt lgkmcnt(0)
	v_cmp_lt_i32_e64 s[14:15], v9, v0
	s_and_b64 s[2:3], vcc, s[14:15]
	s_andn2_b64 s[4:5], s[4:5], exec
	s_and_b64 s[2:3], s[2:3], exec
	s_or_b64 s[4:5], s[4:5], s[2:3]

.LBB0_951:
	s_or_b64 exec, exec, s[14:15]
	s_waitcnt lgkmcnt(0)
	v_xor_b32_e32 v9, 4, v211
	v_cmp_lt_i32_e32 vcc, v9, v3
	s_nop 1
	v_cndmask_b32_e32 v3, v211, v9, vcc
	v_lshlrev_b32_e32 v3, 2, v3
	s_nop 1
	v_mov_b32_dpp v241, v8 row_half_mirror row_mask:0xf bank_mask:0xf
	s_nop 1
	v_mov_b32_dpp v10, v241 quad_perm:[3,2,1,0] row_mask:0xf bank_mask:0xf
	s_nop 1
	v_mov_b32_dpp v241, v0 row_half_mirror row_mask:0xf bank_mask:0xf
	s_nop 1
	v_mov_b32_dpp v9, v241 quad_perm:[3,2,1,0] row_mask:0xf bank_mask:0xf
	s_waitcnt lgkmcnt(1)
	v_cmp_lt_f32_e64 s[4:5], v8, v10
	v_cmp_nlt_f32_e32 vcc, v8, v10
	s_and_saveexec_b64 s[16:17], vcc
	s_cbranch_execz .LBB0_953
	v_cmp_eq_f32_e32 vcc, v8, v10
	s_waitcnt lgkmcnt(0)
	v_cmp_lt_i32_e64 s[14:15], v9, v0
	s_and_b64 s[2:3], vcc, s[14:15]
	s_andn2_b64 s[4:5], s[4:5], exec
	s_and_b64 s[2:3], s[2:3], exec
	s_or_b64 s[4:5], s[4:5], s[2:3]

.LBB0_955:
	s_or_b64 exec, exec, s[14:15]
	v_cmp_ne_u32_e32 vcc, v196, v0
	s_nop 1
	v_cndmask_b32_e32 v8, -1.0, v4, vcc
	v_cmp_ne_u32_e32 vcc, v199, v0
	s_nop 1
	v_cndmask_b32_e32 v5, -1.0, v5, vcc
	v_cmp_ne_u32_e32 vcc, v200, v0
	s_nop 1
	v_cndmask_b32_e32 v6, -1.0, v6, vcc
	v_cmp_ne_u32_e32 vcc, v201, v0
	s_nop 1
	v_cndmask_b32_e32 v7, -1.0, v7, vcc
	v_cmp_gt_f32_e32 vcc, v5, v8
	s_nop 1
	v_cndmask_b32_e32 v4, v8, v5, vcc
	s_waitcnt lgkmcnt(0)
	v_cndmask_b32_e32 v9, v196, v199, vcc
	v_cmp_gt_f32_e32 vcc, v6, v4
	s_nop 1
	v_cndmask_b32_e32 v4, v4, v6, vcc
	v_cndmask_b32_e32 v11, v9, v200, vcc
	v_cmp_gt_f32_e32 vcc, v7, v4
	s_nop 1
	v_cndmask_b32_e32 v9, v4, v7, vcc
	s_nop 1
	v_mov_b32_dpp v10, v9 quad_perm:[1,0,3,2] row_mask:0xf bank_mask:0xf
	v_cndmask_b32_e32 v4, v11, v201, vcc
	s_nop 1
	v_mov_b32_dpp v11, v4 quad_perm:[1,0,3,2] row_mask:0xf bank_mask:0xf
	s_waitcnt lgkmcnt(1)
	v_cmp_lt_f32_e64 s[4:5], v9, v10
	v_cmp_nlt_f32_e32 vcc, v9, v10
	s_and_saveexec_b64 s[16:17], vcc
	s_cbranch_execz .LBB0_957
	v_cmp_eq_f32_e32 vcc, v9, v10
	s_waitcnt lgkmcnt(0)
	v_cmp_lt_i32_e64 s[14:15], v11, v4
	s_and_b64 s[2:3], vcc, s[14:15]
	s_andn2_b64 s[4:5], s[4:5], exec
	s_and_b64 s[2:3], s[2:3], exec
	s_or_b64 s[4:5], s[4:5], s[2:3]

.LBB0_959:
	s_or_b64 exec, exec, s[14:15]
	s_waitcnt lgkmcnt(0)
	s_nop 1
	v_mov_b32_dpp v11, v9 quad_perm:[2,3,0,1] row_mask:0xf bank_mask:0xf
	s_nop 1
	v_mov_b32_dpp v10, v4 quad_perm:[2,3,0,1] row_mask:0xf bank_mask:0xf
	s_waitcnt lgkmcnt(1)
	v_cmp_lt_f32_e64 s[4:5], v9, v11
	v_cmp_nlt_f32_e32 vcc, v9, v11
	s_and_saveexec_b64 s[16:17], vcc
	s_cbranch_execz .LBB0_961
	v_cmp_eq_f32_e32 vcc, v9, v11
	s_waitcnt lgkmcnt(0)
	v_cmp_lt_i32_e64 s[14:15], v10, v4
	s_and_b64 s[2:3], vcc, s[14:15]
	s_andn2_b64 s[4:5], s[4:5], exec
	s_and_b64 s[2:3], s[2:3], exec
	s_or_b64 s[4:5], s[4:5], s[2:3]

.LBB0_963:
	s_or_b64 exec, exec, s[14:15]
	s_nop 1
	v_mov_b32_dpp v241, v9 row_half_mirror row_mask:0xf bank_mask:0xf
	s_nop 1
	v_mov_b32_dpp v11, v241 quad_perm:[3,2,1,0] row_mask:0xf bank_mask:0xf
	s_waitcnt lgkmcnt(1)
	s_nop 1
	v_mov_b32_dpp v241, v4 row_half_mirror row_mask:0xf bank_mask:0xf
	s_nop 1
	v_mov_b32_dpp v10, v241 quad_perm:[3,2,1,0] row_mask:0xf bank_mask:0xf
	s_waitcnt lgkmcnt(1)
	v_cmp_lt_f32_e64 s[4:5], v9, v11
	v_cmp_nlt_f32_e32 vcc, v9, v11
	s_and_saveexec_b64 s[16:17], vcc
	s_cbranch_execz .LBB0_965
	v_cmp_eq_f32_e32 vcc, v9, v11
	s_waitcnt lgkmcnt(0)
	v_cmp_lt_i32_e64 s[14:15], v10, v4
	s_and_b64 s[2:3], vcc, s[14:15]
	s_andn2_b64 s[4:5], s[4:5], exec
	s_and_b64 s[2:3], s[2:3], exec
	s_or_b64 s[4:5], s[4:5], s[2:3]

.LBB0_967:
	s_or_b64 exec, exec, s[14:15]
	v_cmp_ne_u32_e32 vcc, v196, v4
	s_nop 1
	v_cndmask_b32_e32 v8, -1.0, v8, vcc
	v_cmp_ne_u32_e32 vcc, v199, v4
	s_nop 1
	v_cndmask_b32_e32 v9, -1.0, v5, vcc
	v_cmp_ne_u32_e32 vcc, v200, v4
	s_nop 1
	v_cndmask_b32_e32 v6, -1.0, v6, vcc
	v_cmp_ne_u32_e32 vcc, v201, v4
	s_nop 1
	v_cndmask_b32_e32 v7, -1.0, v7, vcc
	v_cmp_gt_f32_e32 vcc, v9, v8
	s_nop 1
	v_cndmask_b32_e32 v5, v8, v9, vcc
	s_waitcnt lgkmcnt(0)
	v_cndmask_b32_e32 v10, v196, v199, vcc
	v_cmp_gt_f32_e32 vcc, v6, v5
	s_nop 1
	v_cndmask_b32_e32 v5, v5, v6, vcc
	v_cndmask_b32_e32 v12, v10, v200, vcc
	v_cmp_gt_f32_e32 vcc, v7, v5
	s_nop 1
	v_cndmask_b32_e32 v10, v5, v7, vcc
	s_nop 1
	v_mov_b32_dpp v11, v10 quad_perm:[1,0,3,2] row_mask:0xf bank_mask:0xf
	v_cndmask_b32_e32 v5, v12, v201, vcc
	s_nop 1
	v_mov_b32_dpp v12, v5 quad_perm:[1,0,3,2] row_mask:0xf bank_mask:0xf
	s_waitcnt lgkmcnt(1)
	v_cmp_lt_f32_e64 s[4:5], v10, v11
	v_cmp_nlt_f32_e32 vcc, v10, v11
	s_and_saveexec_b64 s[16:17], vcc
	s_cbranch_execz .LBB0_969
	v_cmp_eq_f32_e32 vcc, v10, v11
	s_waitcnt lgkmcnt(0)
	v_cmp_lt_i32_e64 s[14:15], v12, v5
	s_and_b64 s[2:3], vcc, s[14:15]
	s_andn2_b64 s[4:5], s[4:5], exec
	s_and_b64 s[2:3], s[2:3], exec
	s_or_b64 s[4:5], s[4:5], s[2:3]

.LBB0_971:
	s_or_b64 exec, exec, s[14:15]
	s_waitcnt lgkmcnt(0)
	s_nop 1
	v_mov_b32_dpp v12, v10 quad_perm:[2,3,0,1] row_mask:0xf bank_mask:0xf
	s_nop 1
	v_mov_b32_dpp v11, v5 quad_perm:[2,3,0,1] row_mask:0xf bank_mask:0xf
	s_waitcnt lgkmcnt(1)
	v_cmp_lt_f32_e64 s[4:5], v10, v12
	v_cmp_nlt_f32_e32 vcc, v10, v12
	s_and_saveexec_b64 s[16:17], vcc
	s_cbranch_execz .LBB0_973
	v_cmp_eq_f32_e32 vcc, v10, v12
	s_waitcnt lgkmcnt(0)
	v_cmp_lt_i32_e64 s[14:15], v11, v5
	s_and_b64 s[2:3], vcc, s[14:15]
	s_andn2_b64 s[4:5], s[4:5], exec
	s_and_b64 s[2:3], s[2:3], exec
	s_or_b64 s[4:5], s[4:5], s[2:3]

.LBB0_975:
	s_or_b64 exec, exec, s[14:15]
	s_nop 1
	v_mov_b32_dpp v241, v10 row_half_mirror row_mask:0xf bank_mask:0xf
	s_nop 1
	v_mov_b32_dpp v12, v241 quad_perm:[3,2,1,0] row_mask:0xf bank_mask:0xf
	s_waitcnt lgkmcnt(1)
	s_nop 1
	v_mov_b32_dpp v241, v5 row_half_mirror row_mask:0xf bank_mask:0xf
	s_nop 1
	v_mov_b32_dpp v11, v241 quad_perm:[3,2,1,0] row_mask:0xf bank_mask:0xf
	s_waitcnt lgkmcnt(1)
	v_cmp_lt_f32_e64 s[4:5], v10, v12
	v_cmp_nlt_f32_e32 vcc, v10, v12
	s_and_saveexec_b64 s[16:17], vcc
	s_cbranch_execz .LBB0_977
	v_cmp_eq_f32_e32 vcc, v10, v12
	s_waitcnt lgkmcnt(0)
	v_cmp_lt_i32_e64 s[14:15], v11, v5
	s_and_b64 s[2:3], vcc, s[14:15]
	s_andn2_b64 s[4:5], s[4:5], exec
	s_and_b64 s[2:3], s[2:3], exec
	s_or_b64 s[4:5], s[4:5], s[2:3]

.LBB0_979:
	s_or_b64 exec, exec, s[14:15]
	v_cmp_ne_u32_e32 vcc, v196, v5
	s_nop 1
	v_cndmask_b32_e32 v8, -1.0, v8, vcc
	v_cmp_ne_u32_e32 vcc, v199, v5
	s_nop 1
	v_cndmask_b32_e32 v9, -1.0, v9, vcc
	v_cmp_ne_u32_e32 vcc, v200, v5
	s_nop 1
	v_cndmask_b32_e32 v10, -1.0, v6, vcc
	v_cmp_ne_u32_e32 vcc, v201, v5
	s_nop 1
	v_cndmask_b32_e32 v7, -1.0, v7, vcc
	v_cmp_gt_f32_e32 vcc, v9, v8
	s_nop 1
	v_cndmask_b32_e32 v6, v8, v9, vcc
	s_waitcnt lgkmcnt(0)
	v_cndmask_b32_e32 v11, v196, v199, vcc
	v_cmp_gt_f32_e32 vcc, v10, v6
	s_nop 1
	v_cndmask_b32_e32 v6, v6, v10, vcc
	v_cndmask_b32_e32 v13, v11, v200, vcc
	v_cmp_gt_f32_e32 vcc, v7, v6
	s_nop 1
	v_cndmask_b32_e32 v11, v6, v7, vcc
	s_nop 1
	v_mov_b32_dpp v12, v11 quad_perm:[1,0,3,2] row_mask:0xf bank_mask:0xf
	v_cndmask_b32_e32 v6, v13, v201, vcc
	s_nop 1
	v_mov_b32_dpp v13, v6 quad_perm:[1,0,3,2] row_mask:0xf bank_mask:0xf
	s_waitcnt lgkmcnt(1)
	v_cmp_lt_f32_e64 s[4:5], v11, v12
	v_cmp_nlt_f32_e32 vcc, v11, v12
	s_and_saveexec_b64 s[16:17], vcc
	s_cbranch_execz .LBB0_981
	v_cmp_eq_f32_e32 vcc, v11, v12
	s_waitcnt lgkmcnt(0)
	v_cmp_lt_i32_e64 s[14:15], v13, v6
	s_and_b64 s[2:3], vcc, s[14:15]
	s_andn2_b64 s[4:5], s[4:5], exec
	s_and_b64 s[2:3], s[2:3], exec
	s_or_b64 s[4:5], s[4:5], s[2:3]

.LBB0_983:
	s_or_b64 exec, exec, s[14:15]
	s_waitcnt lgkmcnt(0)
	s_nop 1
	v_mov_b32_dpp v13, v11 quad_perm:[2,3,0,1] row_mask:0xf bank_mask:0xf
	s_nop 1
	v_mov_b32_dpp v12, v6 quad_perm:[2,3,0,1] row_mask:0xf bank_mask:0xf
	s_waitcnt lgkmcnt(1)
	v_cmp_lt_f32_e64 s[4:5], v11, v13
	v_cmp_nlt_f32_e32 vcc, v11, v13
	s_and_saveexec_b64 s[16:17], vcc
	s_cbranch_execz .LBB0_985
	v_cmp_eq_f32_e32 vcc, v11, v13
	s_waitcnt lgkmcnt(0)
	v_cmp_lt_i32_e64 s[14:15], v12, v6
	s_and_b64 s[2:3], vcc, s[14:15]
	s_andn2_b64 s[4:5], s[4:5], exec
	s_and_b64 s[2:3], s[2:3], exec
	s_or_b64 s[4:5], s[4:5], s[2:3]

.LBB0_987:
	s_or_b64 exec, exec, s[14:15]
	s_nop 1
	v_mov_b32_dpp v241, v11 row_half_mirror row_mask:0xf bank_mask:0xf
	s_nop 1
	v_mov_b32_dpp v13, v241 quad_perm:[3,2,1,0] row_mask:0xf bank_mask:0xf
	s_waitcnt lgkmcnt(1)
	s_nop 1
	v_mov_b32_dpp v241, v6 row_half_mirror row_mask:0xf bank_mask:0xf
	s_nop 1
	v_mov_b32_dpp v12, v241 quad_perm:[3,2,1,0] row_mask:0xf bank_mask:0xf
	s_waitcnt lgkmcnt(1)
	v_cmp_lt_f32_e64 s[4:5], v11, v13
	v_cmp_nlt_f32_e32 vcc, v11, v13
	s_and_saveexec_b64 s[16:17], vcc
	s_cbranch_execz .LBB0_989
	v_cmp_eq_f32_e32 vcc, v11, v13
	s_waitcnt lgkmcnt(0)
	v_cmp_lt_i32_e64 s[14:15], v12, v6
	s_and_b64 s[2:3], vcc, s[14:15]
	s_andn2_b64 s[4:5], s[4:5], exec
	s_and_b64 s[2:3], s[2:3], exec
	s_or_b64 s[4:5], s[4:5], s[2:3]

.LBB0_991:
	s_or_b64 exec, exec, s[14:15]
	v_cmp_ne_u32_e32 vcc, v196, v6
	s_nop 1
	v_cndmask_b32_e32 v8, -1.0, v8, vcc
	v_cmp_ne_u32_e32 vcc, v199, v6
	s_nop 1
	v_cndmask_b32_e32 v9, -1.0, v9, vcc
	v_cmp_ne_u32_e32 vcc, v200, v6
	s_nop 1
	v_cndmask_b32_e32 v10, -1.0, v10, vcc
	v_cmp_ne_u32_e32 vcc, v201, v6
	s_nop 1
	v_cndmask_b32_e32 v7, -1.0, v7, vcc
	v_cmp_gt_f32_e32 vcc, v9, v8
	s_nop 1
	v_cndmask_b32_e32 v8, v8, v9, vcc
	v_cndmask_b32_e32 v9, v196, v199, vcc
	v_cmp_gt_f32_e32 vcc, v10, v8
	s_nop 1
	v_cndmask_b32_e32 v8, v8, v10, vcc
	v_cndmask_b32_e32 v10, v9, v200, vcc
	v_cmp_gt_f32_e32 vcc, v7, v8
	s_nop 1
	v_cndmask_b32_e32 v8, v8, v7, vcc
	s_nop 1
	v_mov_b32_dpp v9, v8 quad_perm:[1,0,3,2] row_mask:0xf bank_mask:0xf
	v_cndmask_b32_e32 v7, v10, v201, vcc
	s_nop 1
	v_mov_b32_dpp v1, v7 quad_perm:[1,0,3,2] row_mask:0xf bank_mask:0xf
	s_waitcnt lgkmcnt(1)
	v_cmp_lt_f32_e64 s[4:5], v8, v9
	v_cmp_nlt_f32_e32 vcc, v8, v9
	s_and_saveexec_b64 s[16:17], vcc
	s_cbranch_execz .LBB0_993
	v_cmp_eq_f32_e32 vcc, v8, v9
	s_waitcnt lgkmcnt(0)
	v_cmp_lt_i32_e64 s[14:15], v1, v7
	s_and_b64 s[2:3], vcc, s[14:15]
	s_andn2_b64 s[4:5], s[4:5], exec
	s_and_b64 s[2:3], s[2:3], exec
	s_or_b64 s[4:5], s[4:5], s[2:3]

.LBB0_995:
	s_or_b64 exec, exec, s[14:15]
	s_nop 1
	v_mov_b32_dpp v9, v8 quad_perm:[2,3,0,1] row_mask:0xf bank_mask:0xf
	s_waitcnt lgkmcnt(1)
	s_nop 1
	v_mov_b32_dpp v1, v7 quad_perm:[2,3,0,1] row_mask:0xf bank_mask:0xf
	s_waitcnt lgkmcnt(1)
	v_cmp_lt_f32_e64 s[4:5], v8, v9
	v_cmp_nlt_f32_e32 vcc, v8, v9
	s_and_saveexec_b64 s[16:17], vcc
	s_cbranch_execz .LBB0_997
	v_cmp_eq_f32_e32 vcc, v8, v9
	s_waitcnt lgkmcnt(0)
	v_cmp_lt_i32_e64 s[14:15], v1, v7
	s_and_b64 s[2:3], vcc, s[14:15]
	s_andn2_b64 s[4:5], s[4:5], exec
	s_and_b64 s[2:3], s[2:3], exec
	s_or_b64 s[4:5], s[4:5], s[2:3]

.LBB0_999:
	s_or_b64 exec, exec, s[14:15]
	s_nop 1
	v_mov_b32_dpp v241, v8 row_half_mirror row_mask:0xf bank_mask:0xf
	s_nop 1
	v_mov_b32_dpp v2, v241 quad_perm:[3,2,1,0] row_mask:0xf bank_mask:0xf
	s_waitcnt lgkmcnt(1)
	s_nop 1
	v_mov_b32_dpp v241, v7 row_half_mirror row_mask:0xf bank_mask:0xf
	s_nop 1
	v_mov_b32_dpp v1, v241 quad_perm:[3,2,1,0] row_mask:0xf bank_mask:0xf
	s_waitcnt lgkmcnt(1)
	v_cmp_lt_f32_e64 s[4:5], v8, v2
	v_cmp_nlt_f32_e32 vcc, v8, v2
	s_and_saveexec_b64 s[16:17], vcc
	s_cbranch_execz .LBB0_1001
	v_cmp_eq_f32_e32 vcc, v8, v2
	s_waitcnt lgkmcnt(0)
	v_cmp_lt_i32_e64 s[14:15], v1, v7
	s_and_b64 s[2:3], vcc, s[14:15]
	s_andn2_b64 s[4:5], s[4:5], exec
	s_and_b64 s[2:3], s[2:3], exec
	s_or_b64 s[4:5], s[4:5], s[2:3]
